# HGRN prefetched operands are landed inside the prefetching item before its trailing stores; the consuming item start no longer waits on vmcnt
# baseline (speedup 1.0000x reference)
.LBB0_188:
	s_or_b64 exec, exec, s[4:5]
	s_waitcnt vmcnt(0)
	v_lshlrev_b32_e32 v176, 1, v125
	v_lshl_add_u64 v[32:33], v[126:127], 0, v[176:177]
	global_load_dwordx2 v[46:47], v[32:33], off offset:1024
	global_load_dwordx2 v[44:45], v[32:33], off offset:1040
	global_load_dwordx2 v[42:43], v[32:33], off offset:1056
	global_load_dwordx2 v[40:41], v[32:33], off offset:1072
	global_load_dwordx2 v[38:39], v[32:33], off offset:1088
	global_load_dwordx2 v[36:37], v[32:33], off offset:1104
	global_load_dwordx2 v[34:35], v[32:33], off offset:1120
	s_nop 0
	global_load_dwordx2 v[32:33], v[32:33], off offset:1136
	v_readlane_b32 s2, v254, 13
	v_readlane_b32 s3, v254, 14
	v_mov_b32_e32 v125, v177
	s_waitcnt vmcnt(7)
	v_lshlrev_b32_e32 v50, 16, v46
	v_and_b32_e32 v51, 0xffff0000, v46
	v_mul_f32_e32 v46, 0xbfb8aa3b, v50
	v_exp_f32_e32 v46, v46
	v_mov_b64_e32 v[48:49], s[2:3]
	v_mad_i64_i32 v[48:49], s[2:3], v136, s67, v[48:49]
	v_add_f32_e32 v46, 1.0, v46
	v_rcp_f32_e32 v52, v46
	v_mul_f32_e32 v46, 0xbfb8aa3b, v51
	v_exp_f32_e32 v46, v46
	v_lshl_add_u64 v[48:49], v[48:49], 0, v[124:125]
	v_add_f32_e32 v46, 1.0, v46
	v_rcp_f32_e32 v53, v46
	s_nop 0
	v_pk_mul_f32 v[50:51], v[52:53], v[50:51]
	s_nop 0
	v_pk_mul_f32 v[16:17], v[16:17], v[50:51]
	s_nop 0
	v_cvt_pk_bf16_f32 v46, v16, v17
	v_lshlrev_b32_e32 v16, 16, v47
	v_and_b32_e32 v17, 0xffff0000, v47
	v_mul_f32_e32 v47, 0xbfb8aa3b, v16
	v_exp_f32_e32 v47, v47
	s_nop 0
	v_add_f32_e32 v47, 1.0, v47
	v_rcp_f32_e32 v50, v47
	v_mul_f32_e32 v47, 0xbfb8aa3b, v17
	v_exp_f32_e32 v47, v47
	s_nop 0
	v_add_f32_e32 v47, 1.0, v47
	v_rcp_f32_e32 v51, v47
	s_nop 0
	v_pk_mul_f32 v[16:17], v[50:51], v[16:17]
	s_nop 0
	v_pk_mul_f32 v[16:17], v[18:19], v[16:17]
	s_waitcnt vmcnt(6)
	v_lshlrev_b32_e32 v18, 16, v44
	v_and_b32_e32 v19, 0xffff0000, v44
	v_mul_f32_e32 v44, 0xbfb8aa3b, v18
	v_exp_f32_e32 v44, v44
	v_cvt_pk_bf16_f32 v47, v16, v17
	v_lshl_add_u64 v[16:17], v[48:49], 0, v[176:177]
	global_store_dwordx2 v[16:17], v[46:47], off
	v_add_f32_e32 v44, 1.0, v44
	v_rcp_f32_e32 v46, v44
	v_mul_f32_e32 v44, 0xbfb8aa3b, v19
	v_exp_f32_e32 v44, v44
	s_nop 0
	v_add_f32_e32 v44, 1.0, v44
	v_rcp_f32_e32 v47, v44
	s_nop 0
	v_pk_mul_f32 v[18:19], v[46:47], v[18:19]
	s_nop 0
	v_pk_mul_f32 v[18:19], v[20:21], v[18:19]
	v_lshlrev_b32_e32 v20, 16, v45
	v_cvt_pk_bf16_f32 v18, v18, v19
	v_mul_f32_e32 v19, 0xbfb8aa3b, v20
	v_exp_f32_e32 v19, v19
	v_and_b32_e32 v21, 0xffff0000, v45
	v_add_f32_e32 v19, 1.0, v19
	v_rcp_f32_e32 v44, v19
	v_mul_f32_e32 v19, 0xbfb8aa3b, v21
	v_exp_f32_e32 v19, v19
	s_nop 0
	v_add_f32_e32 v19, 1.0, v19
	v_rcp_f32_e32 v45, v19
	s_nop 0
	v_pk_mul_f32 v[20:21], v[44:45], v[20:21]
	s_nop 0
	v_pk_mul_f32 v[20:21], v[22:23], v[20:21]
	s_nop 0
	v_cvt_pk_bf16_f32 v19, v20, v21
	global_store_dwordx2 v[16:17], v[18:19], off offset:16
	s_waitcnt vmcnt(7)
	v_lshlrev_b32_e32 v18, 16, v42
	v_and_b32_e32 v19, 0xffff0000, v42
	v_mul_f32_e32 v20, 0xbfb8aa3b, v18
	v_mul_f32_e32 v21, 0xbfb8aa3b, v19
	v_exp_f32_e32 v20, v20
	v_exp_f32_e32 v21, v21
	v_add_f32_e32 v20, 1.0, v20
	v_add_f32_e32 v21, 1.0, v21
	v_rcp_f32_e32 v20, v20
	v_rcp_f32_e32 v21, v21
	s_nop 0
	v_pk_mul_f32 v[18:19], v[20:21], v[18:19]
	s_nop 0
	v_pk_mul_f32 v[18:19], v[24:25], v[18:19]
	v_lshlrev_b32_e32 v20, 16, v43
	v_cvt_pk_bf16_f32 v18, v18, v19
	v_mul_f32_e32 v19, 0xbfb8aa3b, v20
	v_exp_f32_e32 v19, v19
	v_and_b32_e32 v21, 0xffff0000, v43
	v_add_f32_e32 v19, 1.0, v19
	v_rcp_f32_e32 v22, v19
	v_mul_f32_e32 v19, 0xbfb8aa3b, v21
	v_exp_f32_e32 v19, v19
	s_nop 0
	v_add_f32_e32 v19, 1.0, v19
	v_rcp_f32_e32 v23, v19
	s_nop 0
	v_pk_mul_f32 v[20:21], v[22:23], v[20:21]
	s_nop 0
	v_pk_mul_f32 v[20:21], v[26:27], v[20:21]
	s_nop 0
	v_cvt_pk_bf16_f32 v19, v20, v21
	global_store_dwordx2 v[16:17], v[18:19], off offset:32
	s_waitcnt vmcnt(7)
	v_lshlrev_b32_e32 v18, 16, v40
	v_and_b32_e32 v19, 0xffff0000, v40
	v_mul_f32_e32 v20, 0xbfb8aa3b, v18
	v_mul_f32_e32 v21, 0xbfb8aa3b, v19
	v_exp_f32_e32 v20, v20
	v_exp_f32_e32 v21, v21
	v_add_f32_e32 v20, 1.0, v20
	v_add_f32_e32 v21, 1.0, v21
	v_rcp_f32_e32 v20, v20
	v_rcp_f32_e32 v21, v21
	s_nop 0
	v_pk_mul_f32 v[18:19], v[20:21], v[18:19]
	s_nop 0
	v_pk_mul_f32 v[18:19], v[28:29], v[18:19]
	v_lshlrev_b32_e32 v20, 16, v41
	v_cvt_pk_bf16_f32 v18, v18, v19
	v_mul_f32_e32 v19, 0xbfb8aa3b, v20
	v_exp_f32_e32 v19, v19
	v_and_b32_e32 v21, 0xffff0000, v41
	v_add_f32_e32 v19, 1.0, v19
	v_rcp_f32_e32 v22, v19
	v_mul_f32_e32 v19, 0xbfb8aa3b, v21
	v_exp_f32_e32 v19, v19
	s_nop 0
	v_add_f32_e32 v19, 1.0, v19
	v_rcp_f32_e32 v23, v19
	s_nop 0
	v_pk_mul_f32 v[20:21], v[22:23], v[20:21]
	s_nop 0
	v_pk_mul_f32 v[20:21], v[30:31], v[20:21]
	s_nop 0
	v_cvt_pk_bf16_f32 v19, v20, v21
	global_store_dwordx2 v[16:17], v[18:19], off offset:48
	s_waitcnt vmcnt(7)
	v_lshlrev_b32_e32 v18, 16, v38
	v_and_b32_e32 v19, 0xffff0000, v38
	v_mul_f32_e32 v20, 0xbfb8aa3b, v18
	v_mul_f32_e32 v21, 0xbfb8aa3b, v19
	v_exp_f32_e32 v20, v20
	v_exp_f32_e32 v21, v21
	v_add_f32_e32 v20, 1.0, v20
	v_add_f32_e32 v21, 1.0, v21
	v_rcp_f32_e32 v20, v20
	v_rcp_f32_e32 v21, v21
	s_nop 0
	v_pk_mul_f32 v[18:19], v[20:21], v[18:19]
	s_nop 0
	v_pk_mul_f32 v[0:1], v[0:1], v[18:19]
	v_lshlrev_b32_e32 v18, 16, v39
	v_cvt_pk_bf16_f32 v0, v0, v1
	v_mul_f32_e32 v1, 0xbfb8aa3b, v18
	v_exp_f32_e32 v1, v1
	v_and_b32_e32 v19, 0xffff0000, v39
	v_add_f32_e32 v1, 1.0, v1
	v_rcp_f32_e32 v20, v1
	v_mul_f32_e32 v1, 0xbfb8aa3b, v19
	v_exp_f32_e32 v1, v1
	s_nop 0
	v_add_f32_e32 v1, 1.0, v1
	v_rcp_f32_e32 v21, v1
	s_nop 0
	v_pk_mul_f32 v[18:19], v[20:21], v[18:19]
	s_nop 0
	v_pk_mul_f32 v[2:3], v[2:3], v[18:19]
	s_nop 0
	v_cvt_pk_bf16_f32 v1, v2, v3
	global_store_dwordx2 v[16:17], v[0:1], off offset:64
	s_waitcnt vmcnt(7)
	v_lshlrev_b32_e32 v0, 16, v36
	v_and_b32_e32 v1, 0xffff0000, v36
	v_mul_f32_e32 v2, 0xbfb8aa3b, v0
	v_mul_f32_e32 v3, 0xbfb8aa3b, v1
	v_exp_f32_e32 v2, v2
	v_exp_f32_e32 v3, v3
	v_add_f32_e32 v2, 1.0, v2
	v_add_f32_e32 v3, 1.0, v3
	v_rcp_f32_e32 v2, v2
	v_rcp_f32_e32 v3, v3
	s_nop 0
	v_pk_mul_f32 v[0:1], v[2:3], v[0:1]
	s_nop 0
	v_pk_mul_f32 v[0:1], v[4:5], v[0:1]
	v_lshlrev_b32_e32 v2, 16, v37
	v_cvt_pk_bf16_f32 v0, v0, v1
	v_mul_f32_e32 v1, 0xbfb8aa3b, v2
	v_exp_f32_e32 v1, v1
	v_and_b32_e32 v3, 0xffff0000, v37
	v_add_f32_e32 v1, 1.0, v1
	v_rcp_f32_e32 v4, v1
	v_mul_f32_e32 v1, 0xbfb8aa3b, v3
	v_exp_f32_e32 v1, v1
	s_nop 0
	v_add_f32_e32 v1, 1.0, v1
	v_rcp_f32_e32 v5, v1
	s_nop 0
	v_pk_mul_f32 v[2:3], v[4:5], v[2:3]
	s_nop 0
	v_pk_mul_f32 v[2:3], v[6:7], v[2:3]
	s_nop 0
	v_cvt_pk_bf16_f32 v1, v2, v3
	global_store_dwordx2 v[16:17], v[0:1], off offset:80
	s_waitcnt vmcnt(7)
	v_lshlrev_b32_e32 v0, 16, v34
	v_and_b32_e32 v1, 0xffff0000, v34
	v_mul_f32_e32 v2, 0xbfb8aa3b, v0
	v_mul_f32_e32 v3, 0xbfb8aa3b, v1
	v_exp_f32_e32 v2, v2
	v_exp_f32_e32 v3, v3
	v_add_f32_e32 v2, 1.0, v2
	v_add_f32_e32 v3, 1.0, v3
	v_rcp_f32_e32 v2, v2
	v_rcp_f32_e32 v3, v3
	s_nop 0
	v_pk_mul_f32 v[0:1], v[2:3], v[0:1]
	s_nop 0
	v_pk_mul_f32 v[0:1], v[8:9], v[0:1]
	v_lshlrev_b32_e32 v2, 16, v35
	v_cvt_pk_bf16_f32 v0, v0, v1
	v_mul_f32_e32 v1, 0xbfb8aa3b, v2
	v_exp_f32_e32 v1, v1
	v_and_b32_e32 v3, 0xffff0000, v35
	v_add_f32_e32 v1, 1.0, v1
	v_rcp_f32_e32 v4, v1
	v_mul_f32_e32 v1, 0xbfb8aa3b, v3
	v_exp_f32_e32 v1, v1
	s_nop 0
	v_add_f32_e32 v1, 1.0, v1
	v_rcp_f32_e32 v5, v1
	s_nop 0
	v_pk_mul_f32 v[2:3], v[4:5], v[2:3]
	s_nop 0
	v_pk_mul_f32 v[2:3], v[10:11], v[2:3]
	s_nop 0
	v_cvt_pk_bf16_f32 v1, v2, v3
	global_store_dwordx2 v[16:17], v[0:1], off offset:96
	s_waitcnt vmcnt(7)
	v_lshlrev_b32_e32 v0, 16, v32
	v_and_b32_e32 v1, 0xffff0000, v32
	v_mul_f32_e32 v2, 0xbfb8aa3b, v0
	v_mul_f32_e32 v3, 0xbfb8aa3b, v1
	v_exp_f32_e32 v2, v2
	v_exp_f32_e32 v3, v3
	v_add_f32_e32 v2, 1.0, v2
	v_add_f32_e32 v3, 1.0, v3
	v_rcp_f32_e32 v2, v2
	v_rcp_f32_e32 v3, v3
	s_nop 0
	v_pk_mul_f32 v[0:1], v[2:3], v[0:1]
	s_nop 0
	v_pk_mul_f32 v[0:1], v[12:13], v[0:1]
	v_lshlrev_b32_e32 v2, 16, v33
	v_cvt_pk_bf16_f32 v0, v0, v1
	v_mul_f32_e32 v1, 0xbfb8aa3b, v2
	v_exp_f32_e32 v1, v1
	v_and_b32_e32 v3, 0xffff0000, v33
	v_add_f32_e32 v1, 1.0, v1
	v_rcp_f32_e32 v4, v1
	v_mul_f32_e32 v1, 0xbfb8aa3b, v3
	v_exp_f32_e32 v1, v1
	s_nop 0
	v_add_f32_e32 v1, 1.0, v1
	v_rcp_f32_e32 v5, v1
	s_nop 0
	v_pk_mul_f32 v[2:3], v[4:5], v[2:3]
	s_nop 0
	v_pk_mul_f32 v[2:3], v[14:15], v[2:3]
	s_nop 0
	v_cvt_pk_bf16_f32 v1, v2, v3
	global_store_dwordx2 v[16:17], v[0:1], off offset:112

.LBB0_231:
	s_and_b64 vcc, exec, s[2:3]
	s_cbranch_vccz .LBB0_291
	v_mov_b32_e32 v0, v206
	s_addk_i32 s6, 0xfe00
	v_ashrrev_i32_e32 v0, 8, v0
	v_mov_b32_e32 v28, v206
	v_mov_b32_e32 v22, v206
	v_mov_b32_e32 v1, v206
	v_add_u32_e32 v16, s6, v0
	s_movk_i32 s2, 0x100
	v_bfe_u32 v17, v22, 6, 2
	v_ashrrev_i32_e32 v0, 9, v16
	v_cmp_gt_u32_e32 vcc, s2, v1
	v_xor_b32_e32 v1, 3, v17
	v_and_b32_e32 v26, 15, v22
	v_cndmask_b32_e32 v27, v1, v17, vcc
	v_ashrrev_i32_e32 v1, 31, v0
	v_lshlrev_b64 v[24:25], 13, v[0:1]
	v_lshlrev_b32_e32 v0, 6, v16
	s_movk_i32 s2, 0x1fc0
	v_lshlrev_b32_e32 v32, 4, v27
	v_and_or_b32 v20, v0, s2, v24
	v_or_b32_e32 v19, v32, v26
	v_or_b32_e32 v24, v20, v19
	v_mov_b64_e32 v[0:1], s[68:69]
	v_lshrrev_b32_e32 v2, 1, v16
	v_mad_u64_u32 v[0:1], s[2:3], v24, s13, v[0:1]
	v_and_b32_e32 v34, 0xc0, v2
	v_bfe_u32 v23, v22, 4, 2
	v_mad_i32_i24 v1, v25, s13, v1
	v_lshlrev_b32_e32 v176, 1, v34
	v_lshl_add_u64 v[0:1], v[0:1], 0, v[176:177]
	v_lshlrev_b32_e32 v2, 4, v23
	v_mov_b32_e32 v3, v177
	v_lshl_add_u64 v[0:1], v[0:1], 0, v[2:3]
	s_mov_b64 s[2:3], 0x3e80a00
	v_lshl_add_u64 v[2:3], v[0:1], 0, s[2:3]
	s_mov_b32 s2, 0x3e80000
	v_add_co_u32_e32 v0, vcc, s2, v0
	v_mov_b32_e32 v33, v206
	s_nop 0
	v_addc_co_u32_e32 v1, vcc, 0, v1, vcc
	s_nop 0
	v_mov_b64_e32 v[36:37], s[76:77]
	v_bfe_u32 v29, v33, 6, 2
	v_bfe_u32 v30, v33, 2, 6
	v_lshlrev_b32_e32 v8, 4, v33
	v_lshlrev_b32_e32 v18, 4, v29
	v_and_b32_e32 v31, 48, v8
	v_or_b32_e32 v8, v20, v30
	v_or_b32_e32 v20, v20, v18
	v_and_b32_e32 v21, 63, v33
	v_mad_u64_u32 v[8:9], s[2:3], v8, s13, v[36:37]
	v_mad_u64_u32 v[36:37], s[2:3], v20, s13, v[36:37]
	v_mad_i32_i24 v37, v25, s13, v37
	v_lshlrev_b32_e32 v38, 1, v21
	v_mov_b32_e32 v39, v177
	v_lshl_add_u64 v[36:37], v[36:37], 0, v[38:39]
	v_mad_i32_i24 v9, v25, s13, v9
	v_lshl_add_u64 v[52:53], v[36:37], 0, v[176:177]
	v_lshl_add_u64 v[8:9], v[8:9], 0, v[176:177]
	v_lshlrev_b32_e32 v10, 1, v31
	v_mov_b32_e32 v11, v177
	v_lshl_add_u64 v[8:9], v[8:9], 0, v[10:11]
	v_mov_b32_e32 v20, 0
	s_andn2_b64 vcc, exec, s[30:31]
	v_mov_b32_e32 v36, 0
	v_or_b32_e32 v62, v21, v34
	v_lshlrev_b32_e32 v62, 2, v62
	s_cmp_eq_u32 s101, s20
	s_cbranch_scc1 .Lpfh_have
	s_lshl_b32 s100, s20, 1
	s_addk_i32 s100, 0xfe00
	v_lshrrev_b32_e32 v234, 8, v206
	v_add_u32_e32 v234, s100, v234
	v_lshlrev_b32_e32 v235, 6, v234
	v_and_b32_e32 v235, 0x1fc0, v235
	v_lshrrev_b32_e32 v236, 9, v234
	v_lshl_or_b32 v235, v236, 13, v235
	v_bfe_u32 v236, v234, 7, 2
	v_lshlrev_b32_e32 v236, 7, v236
	v_bfe_u32 v237, v206, 6, 2
	v_lshl_add_u32 v238, v237, 4, v235
	v_mul_u32_u24_e32 v238, 0x1400, v238
	v_and_b32_e32 v239, 63, v206
	v_lshl_add_u32 v238, v239, 1, v238
	v_add_u32_e32 v238, v238, v236
	v_lshlrev_b32_e32 v240, 1, v236
	v_lshl_add_u32 v240, v239, 2, v240
	v_lshrrev_b32_e32 v239, 8, v206
	v_mul_u32_u24_e32 v239, 3, v239
	v_xor_b32_e32 v239, v239, v237
	v_lshl_add_u32 v239, v239, 4, v235
	v_and_b32_e32 v241, 15, v206
	v_or_b32_e32 v239, v239, v241
	v_mul_u32_u24_e32 v239, 0x1400, v239
	v_bfe_u32 v241, v206, 4, 2
	v_lshl_add_u32 v239, v241, 4, v239
	v_add_u32_e32 v239, v239, v236
	v_bfe_u32 v241, v206, 2, 6
	v_or_b32_e32 v241, v235, v241
	v_mul_u32_u24_e32 v241, 0x1400, v241
	v_and_b32_e32 v234, 3, v206
	v_lshl_add_u32 v241, v234, 5, v241
	v_add_u32_e32 v241, v241, v236
	global_load_dwordx4 v[188:191], v239, s[76:77] offset:2560
	global_load_dwordx4 v[192:195], v239, s[76:77] offset:2624
	global_load_dwordx4 v[196:199], v241, s[76:77] offset:2048
	global_load_dwordx4 v[200:203], v241, s[76:77] offset:2064
	global_load_ushort v204, v238, s[76:77] offset:1536
	v_add_u32_e32 v238, 0x1400, v238
	global_load_ushort v205, v238, s[76:77] offset:1536
	v_add_u32_e32 v238, 0x1400, v238
	global_load_ushort v186, v238, s[76:77] offset:1536
	v_add_u32_e32 v238, 0x1400, v238
	global_load_ushort v187, v238, s[76:77] offset:1536
	v_add_u32_e32 v238, 0x1400, v238
	global_load_ushort v220, v238, s[76:77] offset:1536
	v_add_u32_e32 v238, 0x1400, v238
	global_load_ushort v221, v238, s[76:77] offset:1536
	v_add_u32_e32 v238, 0x1400, v238
	global_load_ushort v222, v238, s[76:77] offset:1536
	v_add_u32_e32 v238, 0x1400, v238
	global_load_ushort v223, v238, s[76:77] offset:1536
	v_add_u32_e32 v238, 0x1400, v238
	global_load_ushort v224, v238, s[76:77] offset:1536
	v_add_u32_e32 v238, 0x1400, v238
	global_load_ushort v225, v238, s[76:77] offset:1536
	v_add_u32_e32 v238, 0x1400, v238
	global_load_ushort v226, v238, s[76:77] offset:1536
	v_add_u32_e32 v238, 0x1400, v238
	global_load_ushort v227, v238, s[76:77] offset:1536
	v_add_u32_e32 v238, 0x1400, v238
	global_load_ushort v228, v238, s[76:77] offset:1536
	v_add_u32_e32 v238, 0x1400, v238
	global_load_ushort v229, v238, s[76:77] offset:1536
	v_add_u32_e32 v238, 0x1400, v238
	global_load_ushort v230, v238, s[76:77] offset:1536
	v_add_u32_e32 v238, 0x1400, v238
	global_load_ushort v231, v238, s[76:77] offset:1536
	global_load_dword v232, v240, s[52:53]
	global_load_dword v233, v240, s[52:53] offset:1024
	s_waitcnt vmcnt(0)
.Lpfh_have:
	v_mov_b32_e32 v4, v188
	v_mov_b32_e32 v5, v189
	v_mov_b32_e32 v6, v190
	v_mov_b32_e32 v7, v191
	v_mov_b32_e32 v0, v192
	v_mov_b32_e32 v1, v193
	v_mov_b32_e32 v2, v194
	v_mov_b32_e32 v3, v195
	v_mov_b32_e32 v12, v196
	v_mov_b32_e32 v13, v197
	v_mov_b32_e32 v14, v198
	v_mov_b32_e32 v15, v199
	v_mov_b32_e32 v8, v200
	v_mov_b32_e32 v9, v201
	v_mov_b32_e32 v10, v202
	v_mov_b32_e32 v11, v203
	v_mov_b32_e32 v40, v204
	v_mov_b32_e32 v51, v205
	v_mov_b32_e32 v50, v186
	v_mov_b32_e32 v49, v187
	v_mov_b32_e32 v48, v220
	v_mov_b32_e32 v47, v221
	v_mov_b32_e32 v46, v222
	v_mov_b32_e32 v45, v223
	v_mov_b32_e32 v44, v224
	v_mov_b32_e32 v43, v225
	v_mov_b32_e32 v42, v226
	v_mov_b32_e32 v41, v227
	v_mov_b32_e32 v39, v228
	v_mov_b32_e32 v38, v229
	v_mov_b32_e32 v37, v230
	v_mov_b32_e32 v35, v231
	v_mov_b32_e32 v63, v232
	v_mov_b32_e32 v64, v233
	s_add_i32 s101, s20, s72
	s_cmpk_lt_i32 s101, 0x300
	s_cbranch_scc0 .Lpfh_none
	s_lshl_b32 s100, s101, 1
	s_addk_i32 s100, 0xfe00
	v_lshrrev_b32_e32 v234, 8, v206
	v_add_u32_e32 v234, s100, v234
	v_lshlrev_b32_e32 v235, 6, v234
	v_and_b32_e32 v235, 0x1fc0, v235
	v_lshrrev_b32_e32 v236, 9, v234
	v_lshl_or_b32 v235, v236, 13, v235
	v_bfe_u32 v236, v234, 7, 2
	v_lshlrev_b32_e32 v236, 7, v236
	v_bfe_u32 v237, v206, 6, 2
	v_lshl_add_u32 v238, v237, 4, v235
	v_mul_u32_u24_e32 v238, 0x1400, v238
	v_and_b32_e32 v239, 63, v206
	v_lshl_add_u32 v238, v239, 1, v238
	v_add_u32_e32 v238, v238, v236
	v_lshlrev_b32_e32 v240, 1, v236
	v_lshl_add_u32 v240, v239, 2, v240
	v_lshrrev_b32_e32 v239, 8, v206
	v_mul_u32_u24_e32 v239, 3, v239
	v_xor_b32_e32 v239, v239, v237
	v_lshl_add_u32 v239, v239, 4, v235
	v_and_b32_e32 v241, 15, v206
	v_or_b32_e32 v239, v239, v241
	v_mul_u32_u24_e32 v239, 0x1400, v239
	v_bfe_u32 v241, v206, 4, 2
	v_lshl_add_u32 v239, v241, 4, v239
	v_add_u32_e32 v239, v239, v236
	v_bfe_u32 v241, v206, 2, 6
	v_or_b32_e32 v241, v235, v241
	v_mul_u32_u24_e32 v241, 0x1400, v241
	v_and_b32_e32 v234, 3, v206
	v_lshl_add_u32 v241, v234, 5, v241
	v_add_u32_e32 v241, v241, v236
	global_load_dwordx4 v[188:191], v239, s[76:77] offset:2560
	global_load_dwordx4 v[192:195], v239, s[76:77] offset:2624
	global_load_dwordx4 v[196:199], v241, s[76:77] offset:2048
	global_load_dwordx4 v[200:203], v241, s[76:77] offset:2064
	global_load_ushort v204, v238, s[76:77] offset:1536
	v_add_u32_e32 v238, 0x1400, v238
	global_load_ushort v205, v238, s[76:77] offset:1536
	v_add_u32_e32 v238, 0x1400, v238
	global_load_ushort v186, v238, s[76:77] offset:1536
	v_add_u32_e32 v238, 0x1400, v238
	global_load_ushort v187, v238, s[76:77] offset:1536
	v_add_u32_e32 v238, 0x1400, v238
	global_load_ushort v220, v238, s[76:77] offset:1536
	v_add_u32_e32 v238, 0x1400, v238
	global_load_ushort v221, v238, s[76:77] offset:1536
	v_add_u32_e32 v238, 0x1400, v238
	global_load_ushort v222, v238, s[76:77] offset:1536
	v_add_u32_e32 v238, 0x1400, v238
	global_load_ushort v223, v238, s[76:77] offset:1536
	v_add_u32_e32 v238, 0x1400, v238
	global_load_ushort v224, v238, s[76:77] offset:1536
	v_add_u32_e32 v238, 0x1400, v238
	global_load_ushort v225, v238, s[76:77] offset:1536
	v_add_u32_e32 v238, 0x1400, v238
	global_load_ushort v226, v238, s[76:77] offset:1536
	v_add_u32_e32 v238, 0x1400, v238
	global_load_ushort v227, v238, s[76:77] offset:1536
	v_add_u32_e32 v238, 0x1400, v238
	global_load_ushort v228, v238, s[76:77] offset:1536
	v_add_u32_e32 v238, 0x1400, v238
	global_load_ushort v229, v238, s[76:77] offset:1536
	v_add_u32_e32 v238, 0x1400, v238
	global_load_ushort v230, v238, s[76:77] offset:1536
	v_add_u32_e32 v238, 0x1400, v238
	global_load_ushort v231, v238, s[76:77] offset:1536
	global_load_dword v232, v240, s[52:53]
	global_load_dword v233, v240, s[52:53] offset:1024
	s_branch .Lpfh_done

.LBB0_238:
	s_or_b64 exec, exec, s[2:3]
	v_lshlrev_b32_e32 v29, 3, v23
	v_lshl_add_u32 v8, v21, 2, v28
	v_mov_b32_e32 v21, v20
	v_mad_u32_u24 v30, v18, s14, v8
	ds_read_b32 v80, v30
	ds_read_b32 v81, v30 offset:260
	ds_read_b32 v82, v30 offset:520
	ds_read_b32 v83, v30 offset:780
	ds_read_b32 v84, v30 offset:1040
	ds_read_b32 v85, v30 offset:1300
	ds_read_b32 v86, v30 offset:1560
	ds_read_b32 v87, v30 offset:1820
	ds_read_b32 v88, v30 offset:2080
	ds_read_b32 v89, v30 offset:2340
	ds_read_b32 v90, v30 offset:2600
	ds_read_b32 v91, v30 offset:2860
	ds_read_b32 v92, v30 offset:3120
	ds_read_b32 v93, v30 offset:3380
	ds_read_b32 v94, v30 offset:3640
	ds_read_b32 v95, v30 offset:3900
	s_waitcnt lgkmcnt(0)
	v_add_f32_e32 v80, v20, v80
	v_add_f32_e32 v81, v20, v81
	v_add_f32_e32 v82, v20, v82
	v_add_f32_e32 v83, v20, v83
	v_add_f32_e32 v84, v20, v84
	v_add_f32_e32 v85, v20, v85
	v_add_f32_e32 v86, v20, v86
	v_add_f32_e32 v87, v20, v87
	v_add_f32_e32 v88, v20, v88
	v_add_f32_e32 v89, v20, v89
	v_add_f32_e32 v90, v20, v90
	v_add_f32_e32 v91, v20, v91
	v_add_f32_e32 v92, v20, v92
	v_add_f32_e32 v93, v20, v93
	v_add_f32_e32 v94, v20, v94
	v_add_f32_e32 v95, v20, v95
	ds_write_b32 v30, v80
	ds_write_b32 v30, v81 offset:260
	ds_write_b32 v30, v82 offset:520
	ds_write_b32 v30, v83 offset:780
	ds_write_b32 v30, v84 offset:1040
	ds_write_b32 v30, v85 offset:1300
	ds_write_b32 v30, v86 offset:1560
	ds_write_b32 v30, v87 offset:1820
	ds_write_b32 v30, v88 offset:2080
	ds_write_b32 v30, v89 offset:2340
	ds_write_b32 v30, v90 offset:2600
	ds_write_b32 v30, v91 offset:2860
	ds_write_b32 v30, v92 offset:3120
	ds_write_b32 v30, v93 offset:3380
	ds_write_b32 v30, v94 offset:3640
	ds_write_b32 v30, v95 offset:3900
	v_and_b32_e32 v9, 63, v22
	v_lshlrev_b32_e32 v10, 2, v9
	v_add_u32_e32 v8, v28, v10
	s_waitcnt lgkmcnt(0)
	s_barrier
	ds_read_b32 v8, v8 offset:16380
	s_movk_i32 s2, 0x90
	v_mad_u32_u24 v9, v9, s2, v28
	v_lshlrev_b32_e32 v11, 5, v17
	s_mov_b32 s2, 0xac00
	v_add3_u32 v9, v9, v11, s2
	v_mul_u32_u24_e32 v11, 0x1040, v17
	v_add3_u32 v10, v28, v11, v10
	v_add_u32_e32 v72, 0x410, v10
	v_add_u32_e32 v73, 0x820, v10
	v_add_u32_e32 v74, 0xc30, v10
	v_add_u32_e32 v76, 0x4400, v10
	v_add_u32_e32 v77, 0x4810, v10
	v_add_u32_e32 v78, 0x4c20, v10
	v_add_u32_e32 v79, 0x5030, v10
	ds_read2_b32 v[96:97], v76 offset1:65
	ds_read2_b32 v[98:99], v10 offset1:65
	ds_read2_b32 v[100:101], v76 offset0:130 offset1:195
	ds_read2_b32 v[102:103], v10 offset0:130 offset1:195
	ds_read2_b32 v[104:105], v77 offset1:65
	ds_read2_b32 v[106:107], v72 offset1:65
	ds_read2_b32 v[108:109], v77 offset0:130 offset1:195
	ds_read2_b32 v[110:111], v72 offset0:130 offset1:195
	ds_read2_b32 v[112:113], v78 offset1:65
	ds_read2_b32 v[114:115], v73 offset1:65
	ds_read2_b32 v[116:117], v78 offset0:130 offset1:195
	ds_read2_b32 v[118:119], v73 offset0:130 offset1:195
	ds_read2_b32 v[120:121], v79 offset1:65
	ds_read2_b32 v[122:123], v74 offset1:65
	ds_read2_b32 v[124:125], v79 offset0:130 offset1:195
	ds_read2_b32 v[126:127], v74 offset0:130 offset1:195
	s_waitcnt lgkmcnt(0)
	v_sub_f32_e32 v98, v8, v98
	v_sub_f32_e32 v99, v8, v99
	v_sub_f32_e32 v102, v8, v102
	v_sub_f32_e32 v103, v8, v103
	v_mul_f32_e32 v98, 0x3fb8aa3b, v98
	v_mul_f32_e32 v99, 0x3fb8aa3b, v99
	v_mul_f32_e32 v102, 0x3fb8aa3b, v102
	v_mul_f32_e32 v103, 0x3fb8aa3b, v103
	v_exp_f32_e32 v98, v98
	v_exp_f32_e32 v99, v99
	v_exp_f32_e32 v102, v102
	v_exp_f32_e32 v103, v103
	s_nop 0
	v_mul_f32_e32 v98, v96, v98
	v_mul_f32_e32 v99, v97, v99
	v_mul_f32_e32 v102, v100, v102
	v_mul_f32_e32 v103, v101, v103
	v_cvt_pk_bf16_f32 v96, v98, v99
	v_cvt_pk_bf16_f32 v97, v102, v103
	ds_write_b64 v9, v[96:97]
	v_sub_f32_e32 v106, v8, v106
	v_sub_f32_e32 v107, v8, v107
	v_sub_f32_e32 v110, v8, v110
	v_sub_f32_e32 v111, v8, v111
	v_mul_f32_e32 v106, 0x3fb8aa3b, v106
	v_mul_f32_e32 v107, 0x3fb8aa3b, v107
	v_mul_f32_e32 v110, 0x3fb8aa3b, v110
	v_mul_f32_e32 v111, 0x3fb8aa3b, v111
	v_exp_f32_e32 v106, v106
	v_exp_f32_e32 v107, v107
	v_exp_f32_e32 v110, v110
	v_exp_f32_e32 v111, v111
	s_nop 0
	v_mul_f32_e32 v106, v104, v106
	v_mul_f32_e32 v107, v105, v107
	v_mul_f32_e32 v110, v108, v110
	v_mul_f32_e32 v111, v109, v111
	v_cvt_pk_bf16_f32 v104, v106, v107
	v_cvt_pk_bf16_f32 v105, v110, v111
	ds_write_b64 v9, v[104:105] offset:8
	v_sub_f32_e32 v114, v8, v114
	v_sub_f32_e32 v115, v8, v115
	v_sub_f32_e32 v118, v8, v118
	v_sub_f32_e32 v119, v8, v119
	v_mul_f32_e32 v114, 0x3fb8aa3b, v114
	v_mul_f32_e32 v115, 0x3fb8aa3b, v115
	v_mul_f32_e32 v118, 0x3fb8aa3b, v118
	v_mul_f32_e32 v119, 0x3fb8aa3b, v119
	v_exp_f32_e32 v114, v114
	v_exp_f32_e32 v115, v115
	v_exp_f32_e32 v118, v118
	v_exp_f32_e32 v119, v119
	s_nop 0
	v_mul_f32_e32 v114, v112, v114
	v_mul_f32_e32 v115, v113, v115
	v_mul_f32_e32 v118, v116, v118
	v_mul_f32_e32 v119, v117, v119
	v_cvt_pk_bf16_f32 v112, v114, v115
	v_cvt_pk_bf16_f32 v113, v118, v119
	ds_write_b64 v9, v[112:113] offset:16
	v_sub_f32_e32 v122, v8, v122
	v_sub_f32_e32 v123, v8, v123
	v_sub_f32_e32 v126, v8, v126
	v_sub_f32_e32 v127, v8, v127
	v_mul_f32_e32 v122, 0x3fb8aa3b, v122
	v_mul_f32_e32 v123, 0x3fb8aa3b, v123
	v_mul_f32_e32 v126, 0x3fb8aa3b, v126
	v_mul_f32_e32 v127, 0x3fb8aa3b, v127
	v_exp_f32_e32 v122, v122
	v_exp_f32_e32 v123, v123
	v_exp_f32_e32 v126, v126
	v_exp_f32_e32 v127, v127
	s_nop 0
	v_mul_f32_e32 v122, v120, v122
	v_mul_f32_e32 v123, v121, v123
	v_mul_f32_e32 v126, v124, v126
	v_mul_f32_e32 v127, v125, v127
	v_cvt_pk_bf16_f32 v120, v122, v123
	v_cvt_pk_bf16_f32 v121, v126, v127
	ds_write_b64 v9, v[120:121] offset:24
	v_lshl_add_u32 v12, v29, 1, v28
	s_movk_i32 s2, 0x90
	v_mad_u32_u24 v17, v19, s2, v12
	s_waitcnt lgkmcnt(0)
	s_barrier
	ds_read_b128 v[8:11], v17 offset:34816
	v_mad_u32_u24 v18, v26, s2, v12
	ds_read_b128 v[12:15], v18 offset:44032
	ds_read_b128 v[34:37], v18 offset:46336
	ds_read_b128 v[38:41], v18 offset:48640
	ds_read_b128 v[42:45], v18 offset:50944
	s_waitcnt lgkmcnt(3)
	v_mfma_f32_16x16x32_bf16 v[12:15], v[12:15], v[8:11], 0
	v_lshlrev_b32_e32 v30, 2, v23
	v_mov_b32_e32 v33, v177
	v_or_b32_e32 v51, 16, v26
	s_waitcnt lgkmcnt(2)
	v_mfma_f32_16x16x32_bf16 v[34:37], v[34:37], v[8:11], 0
	v_or_b32_e32 v48, 32, v26
	v_or_b32_e32 v31, 48, v26
	v_cmp_lt_u32_sdwa s[4:5], v22, v216 src0_sel:BYTE_0 src1_sel:DWORD
	s_waitcnt lgkmcnt(1)
	v_mfma_f32_16x16x32_bf16 v[38:41], v[38:41], v[8:11], 0
	s_waitcnt lgkmcnt(0)
	v_mfma_f32_16x16x32_bf16 v[8:11], v[42:45], v[8:11], 0
	ds_read_b128 v[42:45], v17 offset:34880
	ds_read_b128 v[52:55], v18 offset:44096
	v_ashrrev_i32_e32 v17, 31, v16
	v_lshlrev_b64 v[20:21], 14, v[16:17]
	s_waitcnt lgkmcnt(0)
	v_mfma_f32_16x16x32_bf16 v[12:15], v[52:55], v[42:45], v[12:15]
	ds_read_b128 v[52:55], v18 offset:46400
	v_lshl_add_u64 v[20:21], s[78:79], 0, v[20:21]
	s_waitcnt lgkmcnt(0)
	v_mfma_f32_16x16x32_bf16 v[34:37], v[52:55], v[42:45], v[34:37]
	ds_read_b128 v[52:55], v18 offset:48704
	s_waitcnt lgkmcnt(0)
	v_mfma_f32_16x16x32_bf16 v[38:41], v[52:55], v[42:45], v[38:41]
	ds_read_b128 v[52:55], v18 offset:51008
	v_or_b32_e32 v66, v32, v26
	v_lshl_or_b32 v66, v66, 6, v30
	v_lshlrev_b32_e32 v66, 2, v66
	v_mov_b32_e32 v67, v177
	v_lshl_add_u64 v[66:67], v[20:21], 0, v[66:67]
	v_or_b32_e32 v18, v32, v30
	v_lshlrev_b32_e32 v18, 6, v18
	v_or_b32_e32 v23, v18, v26
	v_lshlrev_b32_e32 v32, 2, v23
	v_lshl_add_u64 v[32:33], v[20:21], 0, v[32:33]
	s_waitcnt vmcnt(0)
	global_store_dwordx4 v[66:67], v[12:15], off sc1
	global_store_dwordx4 v[66:67], v[34:37], off offset:64 sc1
	global_store_dwordx4 v[66:67], v[38:41], off offset:128 sc1
	s_nop 1
	v_or_b32_e32 v12, v18, v51
	v_lshlrev_b32_e32 v12, 2, v12
	v_mov_b32_e32 v13, v177
	v_lshl_add_u64 v[12:13], v[20:21], 0, v[12:13]
	v_or_b32_e32 v12, v18, v48
	v_lshlrev_b32_e32 v12, 2, v12
	v_mov_b32_e32 v13, v177
	s_waitcnt lgkmcnt(0)
	v_mfma_f32_16x16x32_bf16 v[8:11], v[52:55], v[42:45], v[8:11]
	v_lshl_add_u64 v[12:13], v[20:21], 0, v[12:13]
	s_nop 3
	s_nop 3
	global_store_dwordx4 v[66:67], v[8:11], off offset:192 sc1
	s_nop 1
	v_or_b32_e32 v8, v18, v31
	v_lshlrev_b32_e32 v12, 2, v8
	v_mov_b32_e32 v13, v177
	v_lshl_add_u64 v[12:13], v[20:21], 0, v[12:13]
	s_and_saveexec_b64 s[2:3], s[4:5]
	s_cbranch_execz .LBB0_244
	v_lshlrev_b32_sdwa v8, v213, v22 dst_sel:DWORD dst_unused:UNUSED_PAD src0_sel:DWORD src1_sel:BYTE_0
	v_add_u32_e32 v9, v28, v8
	ds_read_b32 v9, v9 offset:16380
	v_readlane_b32 s4, v254, 21
	v_lshlrev_b64 v[10:11], 8, v[16:17]
	v_readlane_b32 s5, v254, 22
	s_waitcnt lgkmcnt(0)
	v_mul_f32_e32 v9, 0x3fb8aa3b, v9
	v_exp_f32_e32 v12, v9
	v_lshl_add_u64 v[10:11], s[4:5], 0, v[10:11]
	v_mov_b32_e32 v9, v177
	v_lshl_add_u64 v[8:9], v[10:11], 0, v[8:9]
	global_store_dword v[8:9], v12, off
